# attention P.V segment: every MFMA waits only for its own V-fragment pair (counted lgkmcnt) instead of draining LDS at each group of four
# speedup vs baseline: 1.0063x; 1.0014x over previous
.Lat_nme:
	v_add_u32_e32 v184, 0xffffffc0, v184
	v_max_f32_e32 v200, v65, v65
	s_waitcnt lgkmcnt(6)
	v_mfma_f32_32x32x16_bf16 v[32:47], v[204:207], v[220:223], v[32:47]
	ds_read_b64_tr_b16 v[220:221], v165 offset:512
	ds_read_b64_tr_b16 v[222:223], v165 offset:2560
	v_max_f32_e32 v201, v64, v64
	v_max_f32_e32 v200, v201, v200
	v_max3_f32 v200, v200, v66, v67
	v_max3_f32 v200, v200, v68, v69
	v_max3_f32 v200, v200, v70, v71
	s_waitcnt lgkmcnt(6)
	v_mfma_f32_32x32x16_bf16 v[32:47], v[208:211], v[224:227], v[32:47]
	ds_read_b64_tr_b16 v[224:225], v165 offset:4608
	ds_read_b64_tr_b16 v[226:227], v165 offset:6656
	v_max3_f32 v200, v200, v72, v73
	v_max3_f32 v200, v200, v74, v75
	v_max3_f32 v200, v200, v76, v77
	v_max3_f32 v200, v200, v78, v79
	v_max3_f32 v200, v200, v80, v81
	s_waitcnt lgkmcnt(6)
	v_mfma_f32_32x32x16_bf16 v[32:47], v[212:215], v[228:231], v[32:47]
	ds_read_b64_tr_b16 v[228:229], v165 offset:8704
	ds_read_b64_tr_b16 v[230:231], v165 offset:10752
	v_max3_f32 v200, v200, v82, v83
	v_max3_f32 v200, v200, v84, v85
	v_max3_f32 v200, v200, v86, v87
	v_max3_f32 v200, v200, v88, v89
	s_waitcnt lgkmcnt(6)
	v_mfma_f32_32x32x16_bf16 v[32:47], v[216:219], v[232:235], v[32:47]
	ds_read_b64_tr_b16 v[232:233], v165 offset:12800
	ds_read_b64_tr_b16 v[234:235], v165 offset:14848
	v_max3_f32 v200, v200, v90, v91
	v_max3_f32 v200, v200, v92, v93
	v_max3_f32 v200, v200, v94, v95
	v_mov_b32_e32 v201, v200
	s_nop 1
	s_waitcnt lgkmcnt(6)
	v_mfma_f32_32x32x16_bf16 v[48:63], v[204:207], v[220:223], v[48:63]
	ds_read_b64_tr_b16 v[220:221], v165 offset:1024
	ds_read_b64_tr_b16 v[222:223], v165 offset:3072
	v_permlane32_swap_b32_e32 v200, v201
	v_max_f32_e32 v201, v201, v201
	v_max_f32_e32 v200, v200, v200
	v_max_f32_e32 v200, v200, v201
	v_sub_f32_e32 v201, v200, v203
	s_waitcnt lgkmcnt(6)
	v_mfma_f32_32x32x16_bf16 v[48:63], v[208:211], v[224:227], v[48:63]
	ds_read_b64_tr_b16 v[224:225], v165 offset:5120
	ds_read_b64_tr_b16 v[226:227], v165 offset:7168
	v_mul_f32_e32 v201, 0x3db504f3, v201
	v_cmp_ge_f32_e32 vcc, 0x41000000, v201
	v_max_f32_e32 v201, v203, v203
	v_max_f32_e32 v200, v201, v200
	s_waitcnt lgkmcnt(6)
	v_mfma_f32_32x32x16_bf16 v[48:63], v[212:215], v[228:231], v[48:63]
	ds_read_b64_tr_b16 v[228:229], v165 offset:9216
	ds_read_b64_tr_b16 v[230:231], v165 offset:11264
	v_sub_f32_e32 v201, v203, v200
	v_mul_f32_e32 v201, 0x3e0293ee, v201
	v_exp_f32_e32 v201, v201
	s_cmp_eq_u64 vcc, exec
	s_cselect_b64 s[44:45], -1, 0
	s_waitcnt lgkmcnt(6)
	v_mfma_f32_32x32x16_bf16 v[48:63], v[216:219], v[232:235], v[48:63]
	ds_read_b64_tr_b16 v[232:233], v165 offset:13312
	ds_read_b64_tr_b16 v[234:235], v165 offset:15360
	v_cndmask_b32_e64 v202, v201, 1.0, s[44:45]
	v_cndmask_b32_e64 v203, v200, v203, s[44:45]
	v_mul_f32_e32 v248, 0xbe0293ee, v203
	v_pk_fma_f32 v[64:65], v[64:65], s[10:11], v[248:249] op_sel_hi:[1,0,0]
	v_pk_fma_f32 v[66:67], v[66:67], s[10:11], v[248:249] op_sel_hi:[1,0,0]
	s_waitcnt lgkmcnt(6)
	v_mfma_f32_32x32x16_bf16 v[16:31], v[204:207], v[220:223], v[16:31]
	ds_read_b64_tr_b16 v[220:221], v165 offset:1536
	ds_read_b64_tr_b16 v[222:223], v165 offset:3584
	v_pk_fma_f32 v[68:69], v[68:69], s[10:11], v[248:249] op_sel_hi:[1,0,0]
	v_pk_fma_f32 v[70:71], v[70:71], s[10:11], v[248:249] op_sel_hi:[1,0,0]
	v_pk_fma_f32 v[72:73], v[72:73], s[10:11], v[248:249] op_sel_hi:[1,0,0]
	v_pk_fma_f32 v[74:75], v[74:75], s[10:11], v[248:249] op_sel_hi:[1,0,0]
	s_waitcnt lgkmcnt(6)
	v_mfma_f32_32x32x16_bf16 v[16:31], v[208:211], v[224:227], v[16:31]
	ds_read_b64_tr_b16 v[224:225], v165 offset:5632
	ds_read_b64_tr_b16 v[226:227], v165 offset:7680
	v_pk_fma_f32 v[76:77], v[76:77], s[10:11], v[248:249] op_sel_hi:[1,0,0]
	v_pk_fma_f32 v[78:79], v[78:79], s[10:11], v[248:249] op_sel_hi:[1,0,0]
	v_pk_fma_f32 v[80:81], v[80:81], s[10:11], v[248:249] op_sel_hi:[1,0,0]
	v_pk_fma_f32 v[82:83], v[82:83], s[10:11], v[248:249] op_sel_hi:[1,0,0]
	v_pk_fma_f32 v[84:85], v[84:85], s[10:11], v[248:249] op_sel_hi:[1,0,0]
	s_waitcnt lgkmcnt(6)
	v_mfma_f32_32x32x16_bf16 v[16:31], v[212:215], v[228:231], v[16:31]
	ds_read_b64_tr_b16 v[228:229], v165 offset:9728
	ds_read_b64_tr_b16 v[230:231], v165 offset:11776
	v_pk_fma_f32 v[86:87], v[86:87], s[10:11], v[248:249] op_sel_hi:[1,0,0]
	v_pk_fma_f32 v[88:89], v[88:89], s[10:11], v[248:249] op_sel_hi:[1,0,0]
	v_pk_fma_f32 v[90:91], v[90:91], s[10:11], v[248:249] op_sel_hi:[1,0,0]
	v_pk_fma_f32 v[92:93], v[92:93], s[10:11], v[248:249] op_sel_hi:[1,0,0]
	v_pk_fma_f32 v[94:95], v[94:95], s[10:11], v[248:249] op_sel_hi:[1,0,0]
	s_waitcnt lgkmcnt(6)
	v_mfma_f32_32x32x16_bf16 v[16:31], v[216:219], v[232:235], v[16:31]
	ds_read_b64_tr_b16 v[232:233], v165 offset:13824
	ds_read_b64_tr_b16 v[234:235], v165 offset:15872
	v_exp_f32_e32 v64, v64
	v_exp_f32_e32 v65, v65
	v_exp_f32_e32 v66, v66
	v_exp_f32_e32 v67, v67
	s_waitcnt lgkmcnt(6)
	v_mfma_f32_32x32x16_bf16 v[0:15], v[204:207], v[220:223], v[0:15]
	v_exp_f32_e32 v68, v68
	v_exp_f32_e32 v69, v69
	v_pk_add_f32 v[170:171], v[64:65], v[66:67]
	v_exp_f32_e32 v70, v70
	v_exp_f32_e32 v71, v71
	s_waitcnt lgkmcnt(4)
	v_mfma_f32_32x32x16_bf16 v[0:15], v[208:211], v[224:227], v[0:15]
	v_pk_add_f32 v[170:171], v[170:171], v[68:69]
	v_exp_f32_e32 v72, v72
	v_exp_f32_e32 v73, v73
	v_pk_add_f32 v[170:171], v[170:171], v[70:71]
	v_exp_f32_e32 v74, v74
	s_waitcnt lgkmcnt(2)
	v_mfma_f32_32x32x16_bf16 v[0:15], v[212:215], v[228:231], v[0:15]
	v_exp_f32_e32 v75, v75
	v_pk_add_f32 v[170:171], v[170:171], v[72:73]
	v_exp_f32_e32 v76, v76
	v_exp_f32_e32 v77, v77
	s_waitcnt lgkmcnt(0)
	v_mfma_f32_32x32x16_bf16 v[0:15], v[216:219], v[232:235], v[0:15]
	v_pk_add_f32 v[170:171], v[170:171], v[74:75]
	v_exp_f32_e32 v78, v78
	v_exp_f32_e32 v79, v79
	v_pk_add_f32 v[170:171], v[170:171], v[76:77]
	v_cmp_gt_f32_e32 vcc, 1.0, v202
	s_cbranch_vccz .Lat_nre
	s_nop 7
	s_nop 7
	s_and_saveexec_b64 s[4:5], s[0:1]
	ds_write_b32 v183, v202
	s_or_b64 exec, exec, s[4:5]
	s_waitcnt lgkmcnt(0)
	ds_read_b128 v[244:247], v177 offset:0
	s_waitcnt lgkmcnt(0)
	v_pk_mul_f32 v[32:33], v[32:33], v[244:245]
	v_pk_mul_f32 v[34:35], v[34:35], v[246:247]
	v_pk_mul_f32 v[48:49], v[48:49], v[244:245]
	v_pk_mul_f32 v[50:51], v[50:51], v[246:247]
	v_pk_mul_f32 v[16:17], v[16:17], v[244:245]
	v_pk_mul_f32 v[18:19], v[18:19], v[246:247]
	v_pk_mul_f32 v[0:1], v[0:1], v[244:245]
	v_pk_mul_f32 v[2:3], v[2:3], v[246:247]
	ds_read_b128 v[244:247], v177 offset:32
	s_waitcnt lgkmcnt(0)
	v_pk_mul_f32 v[36:37], v[36:37], v[244:245]
	v_pk_mul_f32 v[38:39], v[38:39], v[246:247]
	v_pk_mul_f32 v[52:53], v[52:53], v[244:245]
	v_pk_mul_f32 v[54:55], v[54:55], v[246:247]
	v_pk_mul_f32 v[20:21], v[20:21], v[244:245]
	v_pk_mul_f32 v[22:23], v[22:23], v[246:247]
	v_pk_mul_f32 v[4:5], v[4:5], v[244:245]
	v_pk_mul_f32 v[6:7], v[6:7], v[246:247]
	ds_read_b128 v[244:247], v177 offset:64
	s_waitcnt lgkmcnt(0)
	v_pk_mul_f32 v[40:41], v[40:41], v[244:245]
	v_pk_mul_f32 v[42:43], v[42:43], v[246:247]
	v_pk_mul_f32 v[56:57], v[56:57], v[244:245]
	v_pk_mul_f32 v[58:59], v[58:59], v[246:247]
	v_pk_mul_f32 v[24:25], v[24:25], v[244:245]
	v_pk_mul_f32 v[26:27], v[26:27], v[246:247]
	v_pk_mul_f32 v[8:9], v[8:9], v[244:245]
	v_pk_mul_f32 v[10:11], v[10:11], v[246:247]
	ds_read_b128 v[244:247], v177 offset:96
	s_waitcnt lgkmcnt(0)
	v_pk_mul_f32 v[44:45], v[44:45], v[244:245]
	v_pk_mul_f32 v[46:47], v[46:47], v[246:247]
	v_pk_mul_f32 v[60:61], v[60:61], v[244:245]
	v_pk_mul_f32 v[62:63], v[62:63], v[246:247]
	v_pk_mul_f32 v[28:29], v[28:29], v[244:245]
	v_pk_mul_f32 v[30:31], v[30:31], v[246:247]
	v_pk_mul_f32 v[12:13], v[12:13], v[244:245]
	v_pk_mul_f32 v[14:15], v[14:15], v[246:247]

.Lat_nmo:
	v_add_u32_e32 v184, 0xffffffc0, v184
	v_max_f32_e32 v200, v205, v205
	s_waitcnt lgkmcnt(6)
	v_mfma_f32_32x32x16_bf16 v[32:47], v[64:67], v[80:83], v[32:47]
	ds_read_b64_tr_b16 v[80:81], v165 offset:512
	ds_read_b64_tr_b16 v[82:83], v165 offset:2560
	v_max_f32_e32 v201, v204, v204
	v_max_f32_e32 v200, v201, v200
	v_max3_f32 v200, v200, v206, v207
	v_max3_f32 v200, v200, v208, v209
	v_max3_f32 v200, v200, v210, v211
	s_waitcnt lgkmcnt(6)
	v_mfma_f32_32x32x16_bf16 v[32:47], v[68:71], v[84:87], v[32:47]
	ds_read_b64_tr_b16 v[84:85], v165 offset:4608
	ds_read_b64_tr_b16 v[86:87], v165 offset:6656
	v_max3_f32 v200, v200, v212, v213
	v_max3_f32 v200, v200, v214, v215
	v_max3_f32 v200, v200, v216, v217
	v_max3_f32 v200, v200, v218, v219
	v_max3_f32 v200, v200, v220, v221
	s_waitcnt lgkmcnt(6)
	v_mfma_f32_32x32x16_bf16 v[32:47], v[72:75], v[88:91], v[32:47]
	ds_read_b64_tr_b16 v[88:89], v165 offset:8704
	ds_read_b64_tr_b16 v[90:91], v165 offset:10752
	v_max3_f32 v200, v200, v222, v223
	v_max3_f32 v200, v200, v224, v225
	v_max3_f32 v200, v200, v226, v227
	v_max3_f32 v200, v200, v228, v229
	s_waitcnt lgkmcnt(6)
	v_mfma_f32_32x32x16_bf16 v[32:47], v[76:79], v[92:95], v[32:47]
	ds_read_b64_tr_b16 v[92:93], v165 offset:12800
	ds_read_b64_tr_b16 v[94:95], v165 offset:14848
	v_max3_f32 v200, v200, v230, v231
	v_max3_f32 v200, v200, v232, v233
	v_max3_f32 v200, v200, v234, v235
	v_mov_b32_e32 v201, v200
	s_nop 1
	s_waitcnt lgkmcnt(6)
	v_mfma_f32_32x32x16_bf16 v[48:63], v[64:67], v[80:83], v[48:63]
	ds_read_b64_tr_b16 v[80:81], v165 offset:1024
	ds_read_b64_tr_b16 v[82:83], v165 offset:3072
	v_permlane32_swap_b32_e32 v200, v201
	v_max_f32_e32 v201, v201, v201
	v_max_f32_e32 v200, v200, v200
	v_max_f32_e32 v200, v200, v201
	v_sub_f32_e32 v201, v200, v203
	s_waitcnt lgkmcnt(6)
	v_mfma_f32_32x32x16_bf16 v[48:63], v[68:71], v[84:87], v[48:63]
	ds_read_b64_tr_b16 v[84:85], v165 offset:5120
	ds_read_b64_tr_b16 v[86:87], v165 offset:7168
	v_mul_f32_e32 v201, 0x3db504f3, v201
	v_cmp_ge_f32_e32 vcc, 0x41000000, v201
	v_max_f32_e32 v201, v203, v203
	v_max_f32_e32 v200, v201, v200
	s_waitcnt lgkmcnt(6)
	v_mfma_f32_32x32x16_bf16 v[48:63], v[72:75], v[88:91], v[48:63]
	ds_read_b64_tr_b16 v[88:89], v165 offset:9216
	ds_read_b64_tr_b16 v[90:91], v165 offset:11264
	v_sub_f32_e32 v201, v203, v200
	v_mul_f32_e32 v201, 0x3e0293ee, v201
	v_exp_f32_e32 v201, v201
	s_cmp_eq_u64 vcc, exec
	s_cselect_b64 s[44:45], -1, 0
	s_waitcnt lgkmcnt(6)
	v_mfma_f32_32x32x16_bf16 v[48:63], v[76:79], v[92:95], v[48:63]
	ds_read_b64_tr_b16 v[92:93], v165 offset:13312
	ds_read_b64_tr_b16 v[94:95], v165 offset:15360
	v_cndmask_b32_e64 v202, v201, 1.0, s[44:45]
	v_cndmask_b32_e64 v203, v200, v203, s[44:45]
	v_mul_f32_e32 v248, 0xbe0293ee, v203
	v_pk_fma_f32 v[204:205], v[204:205], s[10:11], v[248:249] op_sel_hi:[1,0,0]
	v_pk_fma_f32 v[206:207], v[206:207], s[10:11], v[248:249] op_sel_hi:[1,0,0]
	s_waitcnt lgkmcnt(6)
	v_mfma_f32_32x32x16_bf16 v[16:31], v[64:67], v[80:83], v[16:31]
	ds_read_b64_tr_b16 v[80:81], v165 offset:1536
	ds_read_b64_tr_b16 v[82:83], v165 offset:3584
	v_pk_fma_f32 v[208:209], v[208:209], s[10:11], v[248:249] op_sel_hi:[1,0,0]
	v_pk_fma_f32 v[210:211], v[210:211], s[10:11], v[248:249] op_sel_hi:[1,0,0]
	v_pk_fma_f32 v[212:213], v[212:213], s[10:11], v[248:249] op_sel_hi:[1,0,0]
	v_pk_fma_f32 v[214:215], v[214:215], s[10:11], v[248:249] op_sel_hi:[1,0,0]
	s_waitcnt lgkmcnt(6)
	v_mfma_f32_32x32x16_bf16 v[16:31], v[68:71], v[84:87], v[16:31]
	ds_read_b64_tr_b16 v[84:85], v165 offset:5632
	ds_read_b64_tr_b16 v[86:87], v165 offset:7680
	v_pk_fma_f32 v[216:217], v[216:217], s[10:11], v[248:249] op_sel_hi:[1,0,0]
	v_pk_fma_f32 v[218:219], v[218:219], s[10:11], v[248:249] op_sel_hi:[1,0,0]
	v_pk_fma_f32 v[220:221], v[220:221], s[10:11], v[248:249] op_sel_hi:[1,0,0]
	v_pk_fma_f32 v[222:223], v[222:223], s[10:11], v[248:249] op_sel_hi:[1,0,0]
	v_pk_fma_f32 v[224:225], v[224:225], s[10:11], v[248:249] op_sel_hi:[1,0,0]
	s_waitcnt lgkmcnt(6)
	v_mfma_f32_32x32x16_bf16 v[16:31], v[72:75], v[88:91], v[16:31]
	ds_read_b64_tr_b16 v[88:89], v165 offset:9728
	ds_read_b64_tr_b16 v[90:91], v165 offset:11776
	v_pk_fma_f32 v[226:227], v[226:227], s[10:11], v[248:249] op_sel_hi:[1,0,0]
	v_pk_fma_f32 v[228:229], v[228:229], s[10:11], v[248:249] op_sel_hi:[1,0,0]
	v_pk_fma_f32 v[230:231], v[230:231], s[10:11], v[248:249] op_sel_hi:[1,0,0]
	v_pk_fma_f32 v[232:233], v[232:233], s[10:11], v[248:249] op_sel_hi:[1,0,0]
	v_pk_fma_f32 v[234:235], v[234:235], s[10:11], v[248:249] op_sel_hi:[1,0,0]
	s_waitcnt lgkmcnt(6)
	v_mfma_f32_32x32x16_bf16 v[16:31], v[76:79], v[92:95], v[16:31]
	ds_read_b64_tr_b16 v[92:93], v165 offset:13824
	ds_read_b64_tr_b16 v[94:95], v165 offset:15872
	v_exp_f32_e32 v204, v204
	v_exp_f32_e32 v205, v205
	v_exp_f32_e32 v206, v206
	v_exp_f32_e32 v207, v207
	s_waitcnt lgkmcnt(6)
	v_mfma_f32_32x32x16_bf16 v[0:15], v[64:67], v[80:83], v[0:15]
	v_exp_f32_e32 v208, v208
	v_exp_f32_e32 v209, v209
	v_pk_add_f32 v[170:171], v[204:205], v[206:207]
	v_exp_f32_e32 v210, v210
	v_exp_f32_e32 v211, v211
	s_waitcnt lgkmcnt(4)
	v_mfma_f32_32x32x16_bf16 v[0:15], v[68:71], v[84:87], v[0:15]
	v_pk_add_f32 v[170:171], v[170:171], v[208:209]
	v_exp_f32_e32 v212, v212
	v_exp_f32_e32 v213, v213
	v_pk_add_f32 v[170:171], v[170:171], v[210:211]
	v_exp_f32_e32 v214, v214
	s_waitcnt lgkmcnt(2)
	v_mfma_f32_32x32x16_bf16 v[0:15], v[72:75], v[88:91], v[0:15]
	v_exp_f32_e32 v215, v215
	v_pk_add_f32 v[170:171], v[170:171], v[212:213]
	v_exp_f32_e32 v216, v216
	v_exp_f32_e32 v217, v217
	s_waitcnt lgkmcnt(0)
	v_mfma_f32_32x32x16_bf16 v[0:15], v[76:79], v[92:95], v[0:15]
	v_pk_add_f32 v[170:171], v[170:171], v[214:215]
	v_exp_f32_e32 v218, v218
	v_exp_f32_e32 v219, v219
	v_pk_add_f32 v[170:171], v[170:171], v[216:217]
	v_cmp_gt_f32_e32 vcc, 1.0, v202
	s_cbranch_vccz .Lat_nro
	s_nop 7
	s_nop 7
	s_and_saveexec_b64 s[4:5], s[0:1]
	ds_write_b32 v183, v202
	s_or_b64 exec, exec, s[4:5]
	s_waitcnt lgkmcnt(0)
	ds_read_b128 v[244:247], v177 offset:0
	s_waitcnt lgkmcnt(0)
	v_pk_mul_f32 v[32:33], v[32:33], v[244:245]
	v_pk_mul_f32 v[34:35], v[34:35], v[246:247]
	v_pk_mul_f32 v[48:49], v[48:49], v[244:245]
	v_pk_mul_f32 v[50:51], v[50:51], v[246:247]
	v_pk_mul_f32 v[16:17], v[16:17], v[244:245]
	v_pk_mul_f32 v[18:19], v[18:19], v[246:247]
	v_pk_mul_f32 v[0:1], v[0:1], v[244:245]
	v_pk_mul_f32 v[2:3], v[2:3], v[246:247]
	ds_read_b128 v[244:247], v177 offset:32
	s_waitcnt lgkmcnt(0)
	v_pk_mul_f32 v[36:37], v[36:37], v[244:245]
	v_pk_mul_f32 v[38:39], v[38:39], v[246:247]
	v_pk_mul_f32 v[52:53], v[52:53], v[244:245]
	v_pk_mul_f32 v[54:55], v[54:55], v[246:247]
	v_pk_mul_f32 v[20:21], v[20:21], v[244:245]
	v_pk_mul_f32 v[22:23], v[22:23], v[246:247]
	v_pk_mul_f32 v[4:5], v[4:5], v[244:245]
	v_pk_mul_f32 v[6:7], v[6:7], v[246:247]
	ds_read_b128 v[244:247], v177 offset:64
	s_waitcnt lgkmcnt(0)
	v_pk_mul_f32 v[40:41], v[40:41], v[244:245]
	v_pk_mul_f32 v[42:43], v[42:43], v[246:247]
	v_pk_mul_f32 v[56:57], v[56:57], v[244:245]
	v_pk_mul_f32 v[58:59], v[58:59], v[246:247]
	v_pk_mul_f32 v[24:25], v[24:25], v[244:245]
	v_pk_mul_f32 v[26:27], v[26:27], v[246:247]
	v_pk_mul_f32 v[8:9], v[8:9], v[244:245]
	v_pk_mul_f32 v[10:11], v[10:11], v[246:247]
	ds_read_b128 v[244:247], v177 offset:96
	s_waitcnt lgkmcnt(0)
	v_pk_mul_f32 v[44:45], v[44:45], v[244:245]
	v_pk_mul_f32 v[46:47], v[46:47], v[246:247]
	v_pk_mul_f32 v[60:61], v[60:61], v[244:245]
	v_pk_mul_f32 v[62:63], v[62:63], v[246:247]
	v_pk_mul_f32 v[28:29], v[28:29], v[244:245]
	v_pk_mul_f32 v[30:31], v[30:31], v[246:247]
	v_pk_mul_f32 v[12:13], v[12:13], v[244:245]
	v_pk_mul_f32 v[14:15], v[14:15], v[246:247]

.Lat_nwo:
	s_mov_b32 s9, s6
	s_mov_b32 s6, s7
	s_mov_b32 s7, s8
	s_mov_b32 s8, s9
	s_add_i32 s12, s12, 2
	s_cmp_lt_u32 s12, s18
	s_cbranch_scc1 .Lat_loop
	v_add_u32_e32 v165, s6, v178
	ds_read_b64_tr_b16 v[220:221], v165 offset:0
	ds_read_b64_tr_b16 v[222:223], v165 offset:2048
	ds_read_b64_tr_b16 v[224:225], v165 offset:4096
	ds_read_b64_tr_b16 v[226:227], v165 offset:6144
	ds_read_b64_tr_b16 v[228:229], v165 offset:8192
	ds_read_b64_tr_b16 v[230:231], v165 offset:10240
	ds_read_b64_tr_b16 v[232:233], v165 offset:12288
	ds_read_b64_tr_b16 v[234:235], v165 offset:14336
	s_waitcnt lgkmcnt(6)
	v_mfma_f32_32x32x16_bf16 v[32:47], v[204:207], v[220:223], v[32:47]
	ds_read_b64_tr_b16 v[220:221], v165 offset:512
	ds_read_b64_tr_b16 v[222:223], v165 offset:2560
	s_waitcnt lgkmcnt(6)
	v_mfma_f32_32x32x16_bf16 v[32:47], v[208:211], v[224:227], v[32:47]
	ds_read_b64_tr_b16 v[224:225], v165 offset:4608
	ds_read_b64_tr_b16 v[226:227], v165 offset:6656
	s_waitcnt lgkmcnt(6)
	v_mfma_f32_32x32x16_bf16 v[32:47], v[212:215], v[228:231], v[32:47]
	ds_read_b64_tr_b16 v[228:229], v165 offset:8704
	ds_read_b64_tr_b16 v[230:231], v165 offset:10752
	s_waitcnt lgkmcnt(6)
	v_mfma_f32_32x32x16_bf16 v[32:47], v[216:219], v[232:235], v[32:47]
	ds_read_b64_tr_b16 v[232:233], v165 offset:12800
	ds_read_b64_tr_b16 v[234:235], v165 offset:14848
	s_waitcnt lgkmcnt(6)
	v_mfma_f32_32x32x16_bf16 v[48:63], v[204:207], v[220:223], v[48:63]
	ds_read_b64_tr_b16 v[220:221], v165 offset:1024
	ds_read_b64_tr_b16 v[222:223], v165 offset:3072
	s_waitcnt lgkmcnt(6)
	v_mfma_f32_32x32x16_bf16 v[48:63], v[208:211], v[224:227], v[48:63]
	ds_read_b64_tr_b16 v[224:225], v165 offset:5120
	ds_read_b64_tr_b16 v[226:227], v165 offset:7168
	s_waitcnt lgkmcnt(6)
	v_mfma_f32_32x32x16_bf16 v[48:63], v[212:215], v[228:231], v[48:63]
	ds_read_b64_tr_b16 v[228:229], v165 offset:9216
	ds_read_b64_tr_b16 v[230:231], v165 offset:11264
	s_waitcnt lgkmcnt(6)
	v_mfma_f32_32x32x16_bf16 v[48:63], v[216:219], v[232:235], v[48:63]
	ds_read_b64_tr_b16 v[232:233], v165 offset:13312
	ds_read_b64_tr_b16 v[234:235], v165 offset:15360
	s_waitcnt lgkmcnt(6)
	v_mfma_f32_32x32x16_bf16 v[16:31], v[204:207], v[220:223], v[16:31]
	ds_read_b64_tr_b16 v[220:221], v165 offset:1536
	ds_read_b64_tr_b16 v[222:223], v165 offset:3584
	s_waitcnt lgkmcnt(6)
	v_mfma_f32_32x32x16_bf16 v[16:31], v[208:211], v[224:227], v[16:31]
	ds_read_b64_tr_b16 v[224:225], v165 offset:5632
	ds_read_b64_tr_b16 v[226:227], v165 offset:7680
	s_waitcnt lgkmcnt(6)
	v_mfma_f32_32x32x16_bf16 v[16:31], v[212:215], v[228:231], v[16:31]
	ds_read_b64_tr_b16 v[228:229], v165 offset:9728
	ds_read_b64_tr_b16 v[230:231], v165 offset:11776
	s_waitcnt lgkmcnt(6)
	v_mfma_f32_32x32x16_bf16 v[16:31], v[216:219], v[232:235], v[16:31]
	ds_read_b64_tr_b16 v[232:233], v165 offset:13824
	ds_read_b64_tr_b16 v[234:235], v165 offset:15872
	s_waitcnt lgkmcnt(6)
	v_mfma_f32_32x32x16_bf16 v[0:15], v[204:207], v[220:223], v[0:15]
	s_waitcnt lgkmcnt(4)
	v_mfma_f32_32x32x16_bf16 v[0:15], v[208:211], v[224:227], v[0:15]
	s_waitcnt lgkmcnt(2)
	v_mfma_f32_32x32x16_bf16 v[0:15], v[212:215], v[228:231], v[0:15]
	s_waitcnt lgkmcnt(0)
	v_mfma_f32_32x32x16_bf16 v[0:15], v[216:219], v[232:235], v[0:15]
	s_nop 7
	s_nop 7
